# best4 + nt on ssm2 ZC block loads and attention Q loads
# baseline (speedup 1.0000x reference)
; template <bool PASS2> __device__ __forceinline__ void ssm2_pass(const Ctx& c, int l) {
;     ...
;         bf16x8 an = *(const bf16x8*)up;
; #pragma unroll 1
;         for (int blk = 0; blk < 8; ++blk) {
;             const bf16x8 a = an;
;             if (blk + 1 < 8) an = *(const bf16x8*)(up + (size_t)(blk + 1) * 32 * 512);
.LBB0_125:
	s_cmp_eq_u32 s42, 0x1c000
	s_cbranch_scc1 .LBB0_127
	global_load_dwordx4 v[130:133], v[162:163], off nt

; template<int THRL> __device__ __forceinline__ void attn_unit(int b,int h,int qb,const bf16*Q,const bf16*__restrict__ K,const bf16*__restrict__ V,const unsigned short*GB,unsigned short*Y,const float*Fcum,int ts,char*shm){
;   int tid_=threadIdx.x; asm volatile("":"+v"(tid_));
;   const int tid=tid_,lane=tid&63,r32=lane&31,hi=lane>>5; const int wid=__builtin_amdgcn_readfirstlane(tid>>6);
;   const long rowbase=(long)b*SEQ; const int q0=qb*QB;
;   const bf16*Qw=Q+(rowbase+q0+wid*QBLK)*PITCH+h*D;
;   const float*Fbh=Fcum+(long)(b*NHEAD+h)*SEQ; float*Fl=(float*)(shm+LDS_F);
;   const bf16*Kh=K+(rowbase+(long)ts*KVBLK)*PITCH+h*D,*Vh=V+(rowbase+(long)ts*KVBLK)*PITCH+h*D;
;   const unsigned lds0=(unsigned)(uintptr_t)shm;
;   float*wsf=(float*)(shm+LDS_WS)+wid*64;
;   const bf16*ksrc=Kh+(long)lane*PITCH+wid*8;
;   const bf16*vsrc=Vh+(long)(16*(wid&3)+(lane>>2))*PITCH+(wid>>2)*32+(lane&3)*8;
;   const unsigned kdst=lds0+LDS_K+wid*1024, vdst=lds0+LDS_V+wid*1024;
;     ...
;   const int vb0=(int)(lds0+LDS_V)+((lane>>4)&1)*32+(lane&3)*8+(4*hi+((lane&15)>>2))*64;
;   const char*Kbase=shm+LDS_K; bf16x8 kf[8];
;   const lds_cptr shm3=(lds_cptr)shm; const lds_cptr kp0=shm3+LDS_K+hi*1024+r32*16; const lds_cptr vp0=shm3+LDS_V+((lane>>4)&1)*32+(lane&3)*8+(4*hi+((lane&15)>>2))*64;
;   const int NT=(q0+QB)/KVBLK-ts;
;   { const int np=(NT+3)>>2;
;     if(wid<np)glds16((const char*)(Fbh+64*ts)+wid*1024+lane*16,(unsigned)__builtin_amdgcn_readfirstlane(lds0+LDS_F+wid*1024));
;     if(wid+8<np)glds16((const char*)(Fbh+64*ts)+(wid+8)*1024+lane*16,(unsigned)__builtin_amdgcn_readfirstlane(lds0+LDS_F+(wid+8)*1024));
;     const unsigned short*gsrc=GB+(rowbase+q0+wid*QBLK+(lane>>3))*PITCH+h*D+(lane&7)*8;
;     #pragma unroll
;     for(int i=0;i<4;++i)glds16(gsrc+(long)i*8*PITCH,(unsigned)__builtin_amdgcn_readfirstlane(lds0+LDS_G+wid*4096+i*1024)); }
;   float nb=Fbh[q0+wid*QBLK+r32];
;   DMA_K(0,0);DMA_V(0,0);DMA_K(1,SLOTB);
;   bf16x8 qr[4];
;   #pragma unroll
;   for(int d0=0;d0<4;++d0)qr[d0]=*reinterpret_cast<const bf16x8*>(&Qw[(long)r32*PITCH+d0*16+hi*8]);
;   float mhat=0.f,l_reg=0.f;f32x16 o[2];o[0]=f32x16{};o[1]=f32x16{};
;     ...
;   const int qrel=wid*QBLK+r32;
;     ...
;   bool resc=false;
;     ...
;   f32x16 pA0,pA1,pB0,pB1;
;   int sl_prev=0,sl_cur=0,sl_next=SLOTB;
;     ...
;   DMA_K(2,2*SLOTB);
;   WAIT_BAR(3);
;   CINIT(pA0,pA1,0);
.LBB0_213:
	s_add_u32 s16, s42, s52
	s_addc_u32 s34, s43, 0
	s_lshl_b32 s21, s31, 5
	s_ashr_i32 s36, s21, 31
	s_add_u32 s50, s16, s21
	s_addc_u32 s51, s34, s36
	s_lshl_b64 s[54:55], s[50:51], 10
	s_add_u32 s16, s89, s54
	s_addc_u32 s36, s3, s55
	s_lshl_b32 s34, s17, 7
	s_add_u32 s54, s16, s34
	s_addc_u32 s55, s36, 0
	s_ashr_i32 s41, s40, 31
	s_lshl_b64 s[60:61], s[40:41], 15
	s_add_u32 s60, s60, s44
	s_addc_u32 s61, s61, s45
	s_lshl_b64 s[60:61], s[60:61], 1
	s_add_u32 s16, s27, s60
	s_addc_u32 s36, s28, s61
	s_add_u32 s62, s16, s34
	s_addc_u32 s63, s36, 0
	s_add_u32 s16, s29, s60
	s_addc_u32 s36, s30, s61
	s_add_u32 s60, s16, s34
	v_lshlrev_b32_e32 v96, 10, v229
	s_addc_u32 s61, s36, 0
	v_lshl_add_u64 v[0:1], s[62:63], 0, v[96:97]
	s_lshl_b32 s62, s31, 3
	s_ashr_i32 s63, s62, 31
	v_lshl_add_u64 v[204:205], s[62:63], 1, v[0:1]
	s_lshl_b32 s16, s31, 4
	v_lshrrev_b32_e32 v0, 2, v229
	v_and_or_b32 v0, s16, 48, v0
	v_lshlrev_b32_e32 v96, 10, v0
	s_ashr_i32 s16, s6, 3
	v_lshl_add_u64 v[0:1], s[60:61], 0, v[96:97]
	s_and_b32 s60, s16, 0xffffffe0
	v_lshlrev_b32_e32 v2, 3, v32
	s_ashr_i32 s61, s60, 31
	v_and_b32_e32 v233, 24, v2
	v_and_b32_e32 v230, 31, v32
	v_lshl_add_u64 v[0:1], s[60:61], 1, v[0:1]
	v_lshlrev_b32_e32 v96, 1, v233
	v_lshrrev_b32_e32 v211, 3, v229
	v_lshrrev_b32_e32 v231, 5, v229
	v_lshl_add_u64 v[206:207], v[0:1], 0, v[96:97]
	v_lshlrev_b32_e32 v0, 4, v230
	v_or_b32_e32 v202, s50, v211
	v_mov_b32_e32 v203, s51
	v_lshl_or_b32 v239, v231, 10, v0
	v_lshlrev_b64 v[0:1], 10, v[202:203]
	v_lshl_add_u64 v[0:1], s[10:11], 0, v[0:1]
	v_and_b32_e32 v2, 56, v2
	s_lshl_b32 s68, s31, 12
	v_lshl_add_u64 v[0:1], v[0:1], 0, s[34:35]
	v_lshlrev_b32_e32 v96, 1, v2
	s_add_i32 s31, s68, 0x18800
	v_lshl_add_u64 v[0:1], v[0:1], 0, v[96:97]
	s_mov_b32 s34, m0
	s_mov_b32 m0, s31
	s_nop 0
	global_load_lds_dwordx4 v[0:1], off
	s_mov_b32 m0, s34
	s_mov_b64 s[60:61], 0x2000
	s_add_i32 s31, s68, 0x18c00
	v_lshl_add_u64 v[2:3], v[0:1], 0, s[60:61]
	s_mov_b32 s34, m0
	s_mov_b32 m0, s31
	s_nop 0
	global_load_lds_dwordx4 v[2:3], off
	s_mov_b32 m0, s34
	s_add_i32 s31, s68, 0x19000
	v_lshl_add_u64 v[2:3], v[0:1], 0, s[96:97]
	s_mov_b32 s34, m0
	s_mov_b32 m0, s31
	s_nop 0
	global_load_lds_dwordx4 v[2:3], off
	s_mov_b32 m0, s34
	s_mov_b64 s[60:61], 0x6000
	s_add_i32 s31, s68, 0x19400
	v_lshl_add_u64 v[0:1], v[0:1], 0, s[60:61]
	s_mov_b32 s34, m0
	s_mov_b32 m0, s31
	s_nop 0
	global_load_lds_dwordx4 v[0:1], off
	s_mov_b32 m0, s34
	s_add_i32 s31, s21, s52
	v_or_b32_e32 v0, s31, v230
	v_ashrrev_i32_e32 v1, 31, v0
	v_lshl_add_u64 v[0:1], v[0:1], 2, s[38:39]
	global_load_dword v33, v[0:1], off
	s_mov_b32 s31, m0
	s_mov_b32 m0, s0
	s_nop 0
	global_load_lds_dwordx4 v[204:205], off
	s_mov_b32 m0, s31
	s_add_i32 s16, s0, 0x6000
	s_mov_b32 s31, m0
	s_mov_b32 m0, s16
	s_nop 0
	global_load_lds_dwordx4 v[206:207], off
	s_mov_b32 m0, s31
	v_lshl_add_u64 v[0:1], v[204:205], 0, s[18:19]
	v_lshlrev_b32_e32 v28, 4, v231
	s_add_i32 s31, s0, 0x2000
	s_mov_b32 s34, m0
	s_mov_b32 m0, s31
	s_nop 0
	global_load_lds_dwordx4 v[0:1], off
	s_mov_b32 m0, s34
	v_lshl_or_b32 v0, v230, 10, v28
	global_load_dwordx4 v[110:113], v0, s[54:55] nt
	global_load_dwordx4 v[106:109], v0, s[54:55] offset:32 nt
	global_load_dwordx4 v[102:105], v0, s[54:55] offset:64 nt
	global_load_dwordx4 v[98:101], v0, s[54:55] offset:96 nt
	v_lshl_add_u64 v[0:1], v[204:205], 0, s[56:57]
	s_add_i32 s31, s0, 0x4000
	s_mov_b32 s34, m0
	s_mov_b32 m0, s31
	s_nop 0
	global_load_lds_dwordx4 v[0:1], off
	s_mov_b32 m0, s34
	s_waitcnt vmcnt(3) lgkmcnt(0)
	s_barrier
	v_or_b32_e32 v0, 0x14800, v28
	s_waitcnt vmcnt(5)
	v_or_b32_e32 v4, 0x14880, v28
	ds_read_b128 v[0:3], v0
	ds_read_b128 v[16:19], v4
	v_or_b32_e32 v4, 0x14820, v28
	v_or_b32_e32 v8, 0x148a0, v28
	ds_read_b128 v[4:7], v4
	ds_read_b128 v[20:23], v8
	v_or_b32_e32 v8, 0x14840, v28
	v_or_b32_e32 v12, 0x148c0, v28
	ds_read_b128 v[8:11], v8
	ds_read_b128 v[24:27], v12
	v_or_b32_e32 v12, 0x14860, v28
	v_or_b32_e32 v28, 0x148e0, v28
	ds_read_b128 v[12:15], v12
	ds_read_b128 v[28:31], v28
	ds_read_b128 v[34:37], v239
	ds_read_b128 v[38:41], v239 offset:512
	v_lshlrev_b32_e32 v232, 2, v231
	v_or_b32_e32 v237, s21, v230
	s_cmp_gt_i32 s12, 4
	s_waitcnt vmcnt(4) lgkmcnt(3)
	v_sub_f32_e32 v15, v33, v15
	v_sub_f32_e32 v14, v33, v14
	v_sub_f32_e32 v13, v33, v13
	v_sub_f32_e32 v12, v33, v12
	v_sub_f32_e32 v11, v33, v11
	v_sub_f32_e32 v10, v33, v10
	v_sub_f32_e32 v9, v33, v9
	v_sub_f32_e32 v8, v33, v8
	v_sub_f32_e32 v7, v33, v7
	v_sub_f32_e32 v6, v33, v6
	v_sub_f32_e32 v5, v33, v5
	v_sub_f32_e32 v4, v33, v4
	v_sub_f32_e32 v3, v33, v3
	v_sub_f32_e32 v2, v33, v2
	v_sub_f32_e32 v1, v33, v1
	v_sub_f32_e32 v0, v33, v0
	s_waitcnt lgkmcnt(2)
	v_sub_f32_e32 v31, v33, v31
	v_sub_f32_e32 v30, v33, v30
	v_sub_f32_e32 v29, v33, v29
	v_sub_f32_e32 v28, v33, v28
	v_sub_f32_e32 v27, v33, v27
	v_sub_f32_e32 v26, v33, v26
	v_sub_f32_e32 v25, v33, v25
	v_sub_f32_e32 v24, v33, v24
	v_sub_f32_e32 v23, v33, v23
	v_sub_f32_e32 v22, v33, v22
	v_sub_f32_e32 v21, v33, v21
	v_sub_f32_e32 v20, v33, v20
	v_sub_f32_e32 v19, v33, v19
	v_sub_f32_e32 v18, v33, v18
	v_sub_f32_e32 v17, v33, v17
	v_sub_f32_e32 v16, v33, v16
	s_waitcnt vmcnt(3) lgkmcnt(1)
	v_mfma_f32_32x32x16_bf16 v[0:15], v[34:37], v[110:113], v[0:15]
	s_waitcnt lgkmcnt(0)
	v_mfma_f32_32x32x16_bf16 v[16:31], v[38:41], v[110:113], v[16:31]
	ds_read_b128 v[34:37], v239 offset:2048
	ds_read_b128 v[38:41], v239 offset:2560
	s_waitcnt vmcnt(2) lgkmcnt(1)
	v_mfma_f32_32x32x16_bf16 v[0:15], v[34:37], v[106:109], v[0:15]
	s_waitcnt lgkmcnt(0)
	v_mfma_f32_32x32x16_bf16 v[16:31], v[38:41], v[106:109], v[16:31]
	ds_read_b128 v[34:37], v239 offset:4096
	ds_read_b128 v[38:41], v239 offset:4608
	s_waitcnt vmcnt(1) lgkmcnt(1)
	v_mfma_f32_32x32x16_bf16 v[0:15], v[34:37], v[102:105], v[0:15]
	s_waitcnt lgkmcnt(0)
	v_mfma_f32_32x32x16_bf16 v[16:31], v[38:41], v[102:105], v[16:31]
	ds_read_b128 v[34:37], v239 offset:6144
	ds_read_b128 v[38:41], v239 offset:6656
	s_waitcnt vmcnt(0) lgkmcnt(1)
	v_mfma_f32_32x32x16_bf16 v[0:15], v[34:37], v[98:101], v[0:15]
	s_waitcnt lgkmcnt(0)
	v_mfma_f32_32x32x16_bf16 v[16:31], v[38:41], v[98:101], v[16:31]
	s_nop 15
	s_nop 7
	s_cbranch_scc1 .LBB0_215
; __device__ __forceinline__ void cmask(f32x16&p0,f32x16&p1,int jb,int qrel,int hi){
;   const float NEG=-INFINITY; int kb=64*jb+4*hi;
;   #pragma unroll
;   for(int r=0;r<16;++r){int kv=kb+(r&3)+8*(r>>2); if(kv>qrel)p0[r]=NEG; if(kv+32>qrel)p1[r]=NEG;}
; }
	s_lshl_b32 s21, s12, 6
	v_subrev_u32_e32 v34, s21, v232
	v_add_u32_e32 v36, 0x120, v34
	v_add_u32_e32 v35, 0x100, v34
	v_cmp_le_i32_e32 vcc, v36, v237
	s_nop 5
	v_cndmask_b32_e32 v16, v227, v16, vcc
	v_cmp_lt_i32_e32 vcc, v35, v237
	s_nop 1
	v_cndmask_b32_e32 v1, v227, v1, vcc
	v_cmp_le_i32_e32 vcc, v35, v237
	v_add_u32_e32 v35, 0x121, v34
	s_nop 0
	v_cndmask_b32_e32 v0, v227, v0, vcc
	v_cmp_le_i32_e32 vcc, v35, v237
	v_add_u32_e32 v35, 0x102, v34
	s_nop 0
	v_cndmask_b32_e32 v17, v227, v17, vcc
	v_cmp_le_i32_e32 vcc, v35, v237
	v_add_u32_e32 v35, 0x122, v34
	s_nop 0
	v_cndmask_b32_e32 v2, v227, v2, vcc
	v_cmp_le_i32_e32 vcc, v35, v237
	v_add_u32_e32 v35, 0x103, v34
	s_nop 0
	v_cndmask_b32_e32 v18, v227, v18, vcc
	v_cmp_le_i32_e32 vcc, v35, v237
	v_add_u32_e32 v35, 0x123, v34
	s_nop 0
	v_cndmask_b32_e32 v3, v227, v3, vcc
	v_cmp_le_i32_e32 vcc, v35, v237
	v_add_u32_e32 v35, 0x108, v34
	s_nop 0
	v_cndmask_b32_e32 v19, v227, v19, vcc
	v_cmp_le_i32_e32 vcc, v35, v237
	v_add_u32_e32 v35, 0x128, v34
	s_nop 0
	v_cndmask_b32_e32 v4, v227, v4, vcc
	v_cmp_le_i32_e32 vcc, v35, v237
	v_add_u32_e32 v35, 0x109, v34
	s_nop 0
	v_cndmask_b32_e32 v20, v227, v20, vcc
	v_cmp_le_i32_e32 vcc, v35, v237
	v_add_u32_e32 v35, 0x129, v34
	s_nop 0
	v_cndmask_b32_e32 v5, v227, v5, vcc
	v_cmp_le_i32_e32 vcc, v35, v237
	v_add_u32_e32 v35, 0x10a, v34
	s_nop 0
	v_cndmask_b32_e32 v21, v227, v21, vcc
	v_cmp_le_i32_e32 vcc, v35, v237
	v_add_u32_e32 v35, 0x12a, v34
	s_nop 0
	v_cndmask_b32_e32 v6, v227, v6, vcc
	v_cmp_le_i32_e32 vcc, v35, v237
	v_add_u32_e32 v35, 0x10b, v34
	s_nop 0
	v_cndmask_b32_e32 v22, v227, v22, vcc
	v_cmp_le_i32_e32 vcc, v35, v237
	v_add_u32_e32 v35, 0x12b, v34
	s_nop 0
	v_cndmask_b32_e32 v7, v227, v7, vcc
	v_cmp_le_i32_e32 vcc, v35, v237
	v_add_u32_e32 v35, 0x110, v34
	s_nop 0
	v_cndmask_b32_e32 v23, v227, v23, vcc
	v_cmp_le_i32_e32 vcc, v35, v237
	v_add_u32_e32 v35, 0x130, v34
	s_nop 0
	v_cndmask_b32_e32 v8, v227, v8, vcc
	v_cmp_le_i32_e32 vcc, v35, v237
	v_add_u32_e32 v35, 0x111, v34
	s_nop 0
	v_cndmask_b32_e32 v24, v227, v24, vcc
	v_cmp_le_i32_e32 vcc, v35, v237
	v_add_u32_e32 v35, 0x131, v34
	s_nop 0
	v_cndmask_b32_e32 v9, v227, v9, vcc
	v_cmp_le_i32_e32 vcc, v35, v237
	v_add_u32_e32 v35, 0x112, v34
	s_nop 0
	v_cndmask_b32_e32 v25, v227, v25, vcc
	v_cmp_le_i32_e32 vcc, v35, v237
	v_add_u32_e32 v35, 0x132, v34
	s_nop 0
	v_cndmask_b32_e32 v10, v227, v10, vcc
	v_cmp_le_i32_e32 vcc, v35, v237
	v_add_u32_e32 v35, 0x113, v34
	s_nop 0
	v_cndmask_b32_e32 v26, v227, v26, vcc
	v_cmp_le_i32_e32 vcc, v35, v237
	v_add_u32_e32 v35, 0x133, v34
	s_nop 0
	v_cndmask_b32_e32 v11, v227, v11, vcc
	v_cmp_le_i32_e32 vcc, v35, v237
	v_add_u32_e32 v35, 0x118, v34
	s_nop 0
	v_cndmask_b32_e32 v27, v227, v27, vcc
	v_cmp_le_i32_e32 vcc, v35, v237
	v_add_u32_e32 v35, 0x138, v34
	s_nop 0
	v_cndmask_b32_e32 v12, v227, v12, vcc
	v_cmp_le_i32_e32 vcc, v35, v237
	v_add_u32_e32 v35, 0x119, v34
	s_nop 0
	v_cndmask_b32_e32 v28, v227, v28, vcc
	v_cmp_le_i32_e32 vcc, v35, v237
	v_add_u32_e32 v35, 0x139, v34
	s_nop 0
	v_cndmask_b32_e32 v13, v227, v13, vcc
	v_cmp_le_i32_e32 vcc, v35, v237
	v_add_u32_e32 v35, 0x11a, v34
	s_nop 0
	v_cndmask_b32_e32 v29, v227, v29, vcc
	v_cmp_le_i32_e32 vcc, v35, v237
	v_add_u32_e32 v35, 0x13a, v34
	s_nop 0
	v_cndmask_b32_e32 v14, v227, v14, vcc
	v_cmp_le_i32_e32 vcc, v35, v237
	v_add_u32_e32 v35, 0x11b, v34
	v_add_u32_e32 v34, 0x13b, v34
	v_cndmask_b32_e32 v30, v227, v30, vcc
	v_cmp_le_i32_e32 vcc, v35, v237
	s_nop 1
	v_cndmask_b32_e32 v15, v227, v15, vcc
	v_cmp_le_i32_e32 vcc, v34, v237
	s_nop 1
	v_cndmask_b32_e32 v31, v227, v31, vcc
